# v31 + attention tile loops (diff pass 1, GQA): loop-invariant inactive-mask computation moved from every tile to the loop exit (loop-edge edit)
# baseline (speedup 1.0000x reference)
; template <int DQ, bool NA, int NQG>
; DI void attn_wg(const half_t* Qp, const half_t* Kp, const half_t* Vp, int q0, bool active, int seg0_start, int seg0_tiles,
;                 int seg1_start, int seg1_tiles, const float* rpb_h, int rq, char* smem, int tid, f16v (&O)[2][NQG]) {
;     ...
;           const h8 kf = *(const h8*)(ksm + (st * 32) * KSTR + ks * 16);
; #pragma unroll
;           for (int qg = 0; qg < NQG; ++qg) S[qg] = __builtin_amdgcn_mfma_f32_32x32x16_f16(kf, qf[qg][ks], S[qg], 0, 0, 0);
;         }
;         if (masked) {
;           const int cb = st * 32;
;           const int dr = krow - rq + 7;
; #pragma unroll
;           for (int qg = 0; qg < NQG; ++qg) {
;             const int qc = qg * 32 + r;
;             const int cs = min(max(qc - 8, 0), 48);
; #pragma unroll
;             for (int i = 0; i < 16; ++i) {
;               const int c = cb + (i & 3) + 8 * (i >> 2) + 4 * h;
;               const bool valid = (c >= cs) && (c < cs + 16);
;               float bias = 0.f;
;               if (valid) bias = rpb_h[dr * 31 + (c - qc + 15)] * LOG2E;
;               S[qg][i] = valid ? S[qg][i] + bias : -1e30f;
;             }
;           }
;         }
;         h4 vf[2][2][2];
; #pragma unroll
;         for (int dvt = 0; dvt < 2; ++dvt)
; #pragma unroll
;           for (int sx = 0; sx < 2; ++sx)
; #pragma unroll
;             for (int hf = 0; hf < 2; ++hf) vf[dvt][sx][hf] = *(const h4*)(vsm + (dvt * 32) * VSTR + st * 32 + sx * 16 + hf * 8);
; #pragma unroll
;         for (int qg = 0; qg < NQG; ++qg) {
;           h8 P[2];
;           float mx = S[qg][0];
; #pragma unroll
;           for (int i = 1; i < 16; ++i) mx = fmaxf(mx, S[qg][i]);
;           mx = fmaxf(mx, __shfl_xor(mx, 32));
;           if (__builtin_amdgcn_ballot_w64(mx > mrun[qg] + 8.f) != 0ull) {
;             const float mnew = fmaxf(mrun[qg], mx);
;             const float alpha = __builtin_amdgcn_exp2f(mrun[qg] - mnew);
;             lrun[qg] *= alpha;
; #pragma unroll
;             for (int dvt = 0; dvt < 2; ++dvt)
; #pragma unroll
;               for (int i = 0; i < 16; ++i) O[dvt][qg][i] *= alpha;
;             mrun[qg] = mnew;
;           }
;           const float mn = mrun[qg];
;           f2 rs2 = {0.f, 0.f};
;           const f2 mn2 = {mn, mn};
; #pragma unroll
;           for (int i = 0; i < 16; i += 2) {
;             const f2 s2 = {S[qg][i], S[qg][i + 1]};
.LBB0_1917:
	s_andn2_b64 vcc, exec, s[14:15]
	s_cbranch_vccnz .LBB0_1924
	s_bitcmp1_b32 s22, 0
	s_cselect_b32 s22, 0x5800, 0
	ds_read_b128 v[198:201], v187 offset:0
	ds_read_b128 v[202:205], v187 offset:32
	ds_read_b128 v[206:209], v187 offset:64
	ds_read_b128 v[210:213], v187 offset:96
	ds_read2_b64 v[138:141], v189 offset0:0 offset1:2
	ds_read2_b64 v[142:145], v189 offset0:4 offset1:6
	ds_read2_b64 v[146:149], v197 offset0:0 offset1:2
	ds_read2_b64 v[150:153], v197 offset0:4 offset1:6
	s_waitcnt lgkmcnt(7)
	v_mfma_f32_32x32x16_f16 v[82:97], v[198:201], v[98:101], 0
	s_waitcnt lgkmcnt(6)
	v_mfma_f32_32x32x16_f16 v[82:97], v[202:205], v[102:105], v[82:97]
	s_waitcnt lgkmcnt(5)
	v_mfma_f32_32x32x16_f16 v[82:97], v[206:209], v[106:109], v[82:97]
	s_waitcnt lgkmcnt(4)
	v_mfma_f32_32x32x16_f16 v[82:97], v[210:213], v[110:113], v[82:97]
	s_nop 11
	v_pk_add_f32 v[82:83], v[82:83], v[194:195] op_sel_hi:[1,0] neg_lo:[0,1] neg_hi:[0,1]
	v_pk_add_f32 v[84:85], v[84:85], v[194:195] op_sel_hi:[1,0] neg_lo:[0,1] neg_hi:[0,1]
	v_exp_f32_e32 v82, v82
	v_exp_f32_e32 v83, v83
	v_pk_add_f32 v[86:87], v[86:87], v[194:195] op_sel_hi:[1,0] neg_lo:[0,1] neg_hi:[0,1]
	v_mfma_f32_32x32x16_f16 v[66:81], v[198:201], v[114:117], 0
	v_exp_f32_e32 v84, v84
	v_exp_f32_e32 v85, v85
	v_pk_add_f32 v[88:89], v[88:89], v[194:195] op_sel_hi:[1,0] neg_lo:[0,1] neg_hi:[0,1]
	v_exp_f32_e32 v86, v86
	v_exp_f32_e32 v87, v87
	v_pk_add_f32 v[90:91], v[90:91], v[194:195] op_sel_hi:[1,0] neg_lo:[0,1] neg_hi:[0,1]
	v_exp_f32_e32 v88, v88
	v_mfma_f32_32x32x16_f16 v[66:81], v[202:205], v[118:121], v[66:81]
	v_exp_f32_e32 v89, v89
	v_pk_add_f32 v[92:93], v[92:93], v[194:195] op_sel_hi:[1,0] neg_lo:[0,1] neg_hi:[0,1]
	v_exp_f32_e32 v90, v90
	v_exp_f32_e32 v91, v91
	v_pk_add_f32 v[94:95], v[94:95], v[194:195] op_sel_hi:[1,0] neg_lo:[0,1] neg_hi:[0,1]
	v_exp_f32_e32 v92, v92
	v_exp_f32_e32 v93, v93
	v_mfma_f32_32x32x16_f16 v[66:81], v[206:209], v[122:125], v[66:81]
	v_pk_add_f32 v[96:97], v[96:97], v[194:195] op_sel_hi:[1,0] neg_lo:[0,1] neg_hi:[0,1]
	v_exp_f32_e32 v94, v94
	v_exp_f32_e32 v95, v95
	v_exp_f32_e32 v96, v96
	v_exp_f32_e32 v97, v97
	v_cvt_pk_f16_f32 v214, v82, v83
	v_cvt_pk_f16_f32 v215, v84, v85
	v_mfma_f32_32x32x16_f16 v[66:81], v[210:213], v[126:129], v[66:81]
	v_cvt_pk_f16_f32 v216, v86, v87
	v_cvt_pk_f16_f32 v217, v88, v89
	v_cvt_pk_f16_f32 v218, v90, v91
	v_cvt_pk_f16_f32 v219, v92, v93
	v_cvt_pk_f16_f32 v220, v94, v95
	v_cvt_pk_f16_f32 v221, v96, v97
	v_pk_add_f32 v[222:223], v[82:83], v[84:85]
	v_pk_add_f32 v[224:225], v[86:87], v[88:89]
	v_pk_add_f32 v[226:227], v[90:91], v[92:93]
	v_pk_add_f32 v[228:229], v[94:95], v[96:97]
	v_pk_add_f32 v[222:223], v[222:223], v[224:225]
	v_pk_add_f32 v[226:227], v[226:227], v[228:229]
	v_pk_add_f32 v[222:223], v[222:223], v[226:227]
	v_add_f32_e32 v222, v222, v223
	v_cmp_lt_f32_e32 vcc, 0x43800000, v222
	s_cbranch_vccnz .Leager_gqa_0

; template <int DQ, bool NA, int NQG>
; DI void attn_wg(const half_t* Qp, const half_t* Kp, const half_t* Vp, int q0, bool active, int seg0_start, int seg0_tiles,
;                 int seg1_start, int seg1_tiles, const float* rpb_h, int rq, char* smem, int tid, f16v (&O)[2][NQG]) {
;     ...
; #pragma unroll
;   for (int qg = 0; qg < NQG; ++qg) {
;     const float lt = lrun[qg] + __shfl_xor(lrun[qg], 32);
;     const float inv = 1.f / lt;
; #pragma unroll
;     for (int dvt = 0; dvt < 2; ++dvt)
; #pragma unroll
;       for (int i = 0; i < 16; ++i) O[dvt][qg][i] *= inv;
;   }
; DI void phase_attn(int l, half_t* big, bool need_ctx, char* smem, int wv_) {
;     ...
;         if (active) store_o<2>(O, orow + 3 * 256, lane);
.LBB0_1930:
	v_cndmask_b32_e64 v66, 0, 1, s[14:15]
	v_cmp_ne_u32_e64 s[6:7], 1, v66
	v_cmp_lt_i32_e32 vcc, v242, v241
	s_mov_b64 s[22:23], 0
	s_mov_b64 s[8:9], 0
	v_cndmask_b32_e32 v66, v240, v242, vcc
	v_lshlrev_b32_e32 v67, 2, v66
	ds_bpermute_b32 v66, v67, v183
	ds_bpermute_b32 v67, v67, v1
	s_and_b64 vcc, exec, s[6:7]
	s_cbranch_vccnz .LBB0_1932
	s_waitcnt lgkmcnt(0)
	v_add_f32_e32 v1, v1, v67
	v_div_scale_f32 v67, s[6:7], v1, v1, 1.0
	v_rcp_f32_e32 v68, v67
	v_div_scale_f32 v69, vcc, 1.0, v1, 1.0
	s_mov_b64 s[8:9], -1
	v_fma_f32 v70, -v67, v68, 1.0
	v_fmac_f32_e32 v68, v70, v68
	v_mul_f32_e32 v70, v69, v68
	v_fma_f32 v71, -v67, v70, v69
	v_fmac_f32_e32 v70, v71, v68
	v_fma_f32 v67, -v67, v70, v69
	v_div_fmas_f32 v67, v67, v68, v70
	v_div_fixup_f32 v68, v67, v1, 1.0
	v_add_f32_e32 v1, v183, v66
	v_pk_mul_f32 v[116:117], v[40:41], v[68:69] op_sel_hi:[1,0]
	v_div_scale_f32 v40, s[6:7], v1, v1, 1.0
	v_rcp_f32_e32 v41, v40
	v_pk_mul_f32 v[138:139], v[34:35], v[68:69] op_sel_hi:[1,0]
	s_waitcnt vmcnt(0)
	v_pk_mul_f32 v[134:135], v[36:37], v[68:69] op_sel_hi:[1,0]
	s_add_u32 s6, s27, 0x600
	v_fma_f32 v34, -v40, v41, 1.0
	v_fmac_f32_e32 v41, v34, v41
	v_div_scale_f32 v34, vcc, 1.0, v1, 1.0
	v_mul_f32_e32 v35, v34, v41
	v_fma_f32 v36, -v40, v35, v34
	v_fmac_f32_e32 v35, v36, v41
	v_fma_f32 v34, -v40, v35, v34
	v_div_fmas_f32 v34, v34, v41, v35
	v_div_fixup_f32 v34, v34, v1, 1.0
	v_pk_mul_f32 v[80:81], v[64:65], v[68:69] op_sel_hi:[1,0]
	v_pk_mul_f32 v[82:83], v[62:63], v[68:69] op_sel_hi:[1,0]
	v_pk_mul_f32 v[84:85], v[60:61], v[68:69] op_sel_hi:[1,0]
	v_pk_mul_f32 v[86:87], v[58:59], v[68:69] op_sel_hi:[1,0]
	v_pk_mul_f32 v[88:89], v[56:57], v[68:69] op_sel_hi:[1,0]
	v_pk_mul_f32 v[90:91], v[54:55], v[68:69] op_sel_hi:[1,0]
	v_pk_mul_f32 v[92:93], v[52:53], v[68:69] op_sel_hi:[1,0]
	v_pk_mul_f32 v[94:95], v[50:51], v[68:69] op_sel_hi:[1,0]
	v_pk_mul_f32 v[100:101], v[48:49], v[68:69] op_sel_hi:[1,0]
	v_pk_mul_f32 v[102:103], v[46:47], v[68:69] op_sel_hi:[1,0]
	v_pk_mul_f32 v[108:109], v[44:45], v[68:69] op_sel_hi:[1,0]
	v_pk_mul_f32 v[110:111], v[42:43], v[68:69] op_sel_hi:[1,0]
	v_pk_mul_f32 v[118:119], v[38:39], v[68:69] op_sel_hi:[1,0]
	v_pk_mul_f32 v[96:97], v[32:33], v[34:35] op_sel_hi:[1,0]
	v_pk_mul_f32 v[98:99], v[30:31], v[34:35] op_sel_hi:[1,0]
	v_pk_mul_f32 v[104:105], v[28:29], v[34:35] op_sel_hi:[1,0]
	v_pk_mul_f32 v[106:107], v[26:27], v[34:35] op_sel_hi:[1,0]
	v_pk_mul_f32 v[112:113], v[24:25], v[34:35] op_sel_hi:[1,0]
	v_pk_mul_f32 v[114:115], v[22:23], v[34:35] op_sel_hi:[1,0]
	v_pk_mul_f32 v[120:121], v[20:21], v[34:35] op_sel_hi:[1,0]
	v_pk_mul_f32 v[122:123], v[18:19], v[34:35] op_sel_hi:[1,0]
	v_pk_mul_f32 v[124:125], v[16:17], v[34:35] op_sel_hi:[1,0]
	v_pk_mul_f32 v[126:127], v[14:15], v[34:35] op_sel_hi:[1,0]
	v_pk_mul_f32 v[128:129], v[12:13], v[34:35] op_sel_hi:[1,0]
	v_pk_mul_f32 v[130:131], v[10:11], v[34:35] op_sel_hi:[1,0]
	v_pk_mul_f32 v[132:133], v[8:9], v[34:35] op_sel_hi:[1,0]
	v_pk_mul_f32 v[136:137], v[6:7], v[34:35] op_sel_hi:[1,0]
	v_pk_mul_f32 v[140:141], v[4:5], v[34:35] op_sel_hi:[1,0]
	v_pk_mul_f32 v[142:143], v[2:3], v[34:35] op_sel_hi:[1,0]
	s_addc_u32 s7, s28, 0

; template <int DQ, bool NA, int NQG>
; DI void attn_wg(const half_t* Qp, const half_t* Kp, const half_t* Vp, int q0, bool active, int seg0_start, int seg0_tiles,
;                 int seg1_start, int seg1_tiles, const float* rpb_h, int rq, char* smem, int tid, f16v (&O)[2][NQG]) {
;     ...
;     const half_t* ksm = (const half_t*)(smem + (it & 1) * ATT_STAGE) + r * KSTR + h * 8;
;     const half_t* vsm = (const half_t*)(smem + (it & 1) * ATT_STAGE + ATT_VOFF) + r * VSTR + h * 4;
;     const bool masked = NA && it < seg0_tiles;
;     const int krow = k0 >> 6;
;     const bool need = active && (!masked || (krow >= r0w && krow < r0w + 8));
;     if (need) {
; #pragma unroll 1
;       for (int st = 0; st < 2; ++st) {
;         f16v S[NQG];
; #pragma unroll
;         for (int qg = 0; qg < NQG; ++qg)
; #pragma unroll
;           for (int i = 0; i < 16; ++i) S[qg][i] = 0.f;
; #pragma unroll
;         for (int ks = 0; ks < NKS; ++ks) {
;           const h8 kf = *(const h8*)(ksm + (st * 32) * KSTR + ks * 16);
; #pragma unroll
;           for (int qg = 0; qg < NQG; ++qg) S[qg] = __builtin_amdgcn_mfma_f32_32x32x16_f16(kf, qf[qg][ks], S[qg], 0, 0, 0);
.LBB0_2039:
	s_andn2_b64 vcc, exec, s[14:15]
	s_cbranch_vccnz .LBB0_2046
	s_cmp_eq_u32 s18, 0
	s_cselect_b32 s19, 1, 0
	s_bitcmp1_b32 s18, 0
	s_cselect_b32 s18, 0x5800, 0
	s_cmp_lg_u32 s19, 0
	s_cbranch_scc0 .Lnoinit_diff1c
	v_mov_b32_e32 v196, 0
	v_mov_b32_e32 v197, 0
	v_mov_b32_e32 v198, 0
	v_mov_b32_e32 v199, 0
	v_mov_b32_e32 v200, 0
	v_mov_b32_e32 v201, 0
	v_mov_b32_e32 v202, 0
	v_mov_b32_e32 v203, 0
	v_mov_b32_e32 v204, 0
	v_mov_b32_e32 v205, 0
	v_mov_b32_e32 v206, 0
	v_mov_b32_e32 v207, 0
	v_mov_b32_e32 v208, 0
	v_mov_b32_e32 v209, 0
	v_mov_b32_e32 v210, 0
	v_mov_b32_e32 v211, 0
	v_mov_b32_e32 v212, 0
	v_mov_b32_e32 v213, 0
	v_mov_b32_e32 v214, 0
	v_mov_b32_e32 v215, 0
	v_mov_b32_e32 v216, 0
	v_mov_b32_e32 v217, 0
	v_mov_b32_e32 v218, 0
	v_mov_b32_e32 v219, 0
	v_mov_b32_e32 v220, 0
	v_mov_b32_e32 v221, 0
	v_mov_b32_e32 v222, 0
	v_mov_b32_e32 v223, 0
	v_mov_b32_e32 v224, 0
	v_mov_b32_e32 v225, 0
	v_mov_b32_e32 v226, 0
	v_mov_b32_e32 v227, 0

; template <int DQ, bool NA, int NQG>
; DI void attn_wg(const half_t* Qp, const half_t* Kp, const half_t* Vp, int q0, bool active, int seg0_start, int seg0_tiles,
;                 int seg1_start, int seg1_tiles, const float* rpb_h, int rq, char* smem, int tid, f16v (&O)[2][NQG]) {
;     ...
; #pragma unroll
;   for (int qg = 0; qg < NQG; ++qg) {
;     const float lt = lrun[qg] + __shfl_xor(lrun[qg], 32);
;     const float inv = 1.f / lt;
; #pragma unroll
;     for (int dvt = 0; dvt < 2; ++dvt)
; #pragma unroll
;       for (int i = 0; i < 16; ++i) O[dvt][qg][i] *= inv;
;   }
; }
; DI void phase_attn(int l, half_t* big, bool need_ctx, char* smem, int wv_) {
;     ...
;         for (int dvt = 0; dvt < 2; ++dvt)
; #pragma unroll
;           for (int qg = 0; qg < 2; ++qg)
; #pragma unroll
;             for (int i = 0; i < 16; ++i) stash[((dvt * 2 + qg) * 16 + i) * 64 + lane] = (half_t)O[dvt][qg][i];
;         attn_wg<32, false, 2>(big + B_QDF + (size_t)(b * 8 + hh * 2 + 1) * TOK * 32, big + B_KDF + (size_t)(b * 8 + hh * 2 + 1) * TOK * 32,
.LBB0_2052:
	v_cndmask_b32_e64 v2, 0, 1, s[14:15]
	v_cmp_ne_u32_e64 s[6:7], 1, v2
	v_cmp_lt_i32_e32 vcc, v242, v241
	s_nop 1
	v_cndmask_b32_e32 v2, v240, v242, vcc
	v_lshlrev_b32_e32 v150, 2, v2
	ds_bpermute_b32 v2, v150, v149
	s_waitcnt lgkmcnt(0)
	v_add_f32_e32 v2, v149, v2
	v_div_scale_f32 v3, s[14:15], v2, v2, 1.0
	v_rcp_f32_e32 v4, v3
	s_nop 0
	v_fma_f32 v5, -v3, v4, 1.0
	v_fmac_f32_e32 v4, v5, v4
	v_div_scale_f32 v5, vcc, 1.0, v2, 1.0
	v_mul_f32_e32 v6, v5, v4
	v_fma_f32 v7, -v3, v6, v5
	v_fmac_f32_e32 v6, v7, v4
	v_fma_f32 v3, -v3, v6, v5
	v_div_fmas_f32 v3, v3, v4, v6
	v_div_fixup_f32 v2, v3, v2, 1.0
	ds_bpermute_b32 v3, v150, v1
	s_waitcnt lgkmcnt(0)
	v_add_f32_e32 v1, v1, v3
	v_div_scale_f32 v3, s[14:15], v1, v1, 1.0
	v_rcp_f32_e32 v4, v3
	s_or_b32 s14, s20, 1
	v_fma_f32 v5, -v3, v4, 1.0
	v_fmac_f32_e32 v4, v5, v4
	v_div_scale_f32 v5, vcc, 1.0, v1, 1.0
	v_mul_f32_e32 v6, v5, v4
	v_fma_f32 v7, -v3, v6, v5
	v_fmac_f32_e32 v6, v7, v4
	v_fma_f32 v3, -v3, v6, v5
	v_div_fmas_f32 v3, v3, v4, v6
	v_div_fixup_f32 v1, v3, v1, 1.0
	v_fma_mixlo_f16 v3, v64, v2, 0
	ds_write_b16 v243, v3 offset:49152
	v_fma_mixlo_f16 v3, v65, v2, 0
	ds_write_b16 v243, v3 offset:49280
	v_fma_mixlo_f16 v3, v66, v2, 0
	ds_write_b16 v243, v3 offset:49408
	v_fma_mixlo_f16 v3, v67, v2, 0
	ds_write_b16 v243, v3 offset:49536
	v_fma_mixlo_f16 v3, v68, v2, 0
	ds_write_b16 v243, v3 offset:49664
	v_fma_mixlo_f16 v3, v69, v2, 0
	ds_write_b16 v243, v3 offset:49792
	v_fma_mixlo_f16 v3, v70, v2, 0
	ds_write_b16 v243, v3 offset:49920
	v_fma_mixlo_f16 v3, v71, v2, 0
	ds_write_b16 v243, v3 offset:50048
	v_fma_mixlo_f16 v3, v72, v2, 0
	ds_write_b16 v243, v3 offset:50176
	v_fma_mixlo_f16 v3, v73, v2, 0
	ds_write_b16 v243, v3 offset:50304
	v_fma_mixlo_f16 v3, v74, v2, 0
	ds_write_b16 v243, v3 offset:50432
	v_fma_mixlo_f16 v3, v75, v2, 0
	ds_write_b16 v243, v3 offset:50560
	v_fma_mixlo_f16 v3, v76, v2, 0
	ds_write_b16 v243, v3 offset:50688
	v_fma_mixlo_f16 v3, v77, v2, 0
	ds_write_b16 v243, v3 offset:50816
	v_fma_mixlo_f16 v3, v78, v2, 0
	ds_write_b16 v243, v3 offset:50944
	v_fma_mixlo_f16 v3, v79, v2, 0
	ds_write_b16 v243, v3 offset:51072
	v_fma_mixlo_f16 v3, v48, v1, 0
	ds_write_b16 v243, v3 offset:51200
	v_fma_mixlo_f16 v3, v49, v1, 0
	ds_write_b16 v243, v3 offset:51328
	v_fma_mixlo_f16 v3, v50, v1, 0
	ds_write_b16 v243, v3 offset:51456
	v_fma_mixlo_f16 v3, v51, v1, 0
	ds_write_b16 v243, v3 offset:51584
	v_fma_mixlo_f16 v3, v52, v1, 0
	ds_write_b16 v243, v3 offset:51712
	v_fma_mixlo_f16 v3, v53, v1, 0
	ds_write_b16 v243, v3 offset:51840
	v_fma_mixlo_f16 v3, v54, v1, 0
	ds_write_b16 v243, v3 offset:51968
	v_fma_mixlo_f16 v3, v55, v1, 0
	ds_write_b16 v243, v3 offset:52096
	v_fma_mixlo_f16 v3, v56, v1, 0
	ds_write_b16 v243, v3 offset:52224
	v_fma_mixlo_f16 v3, v57, v1, 0
	ds_write_b16 v243, v3 offset:52352
	v_fma_mixlo_f16 v3, v58, v1, 0
	ds_write_b16 v243, v3 offset:52480
	v_fma_mixlo_f16 v3, v59, v1, 0
	ds_write_b16 v243, v3 offset:52608
	v_fma_mixlo_f16 v3, v60, v1, 0
	ds_write_b16 v243, v3 offset:52736
	v_fma_mixlo_f16 v3, v61, v1, 0
	ds_write_b16 v243, v3 offset:52864
	v_fma_mixlo_f16 v3, v62, v1, 0
	ds_write_b16 v243, v3 offset:52992
	v_fma_mixlo_f16 v3, v63, v1, 0
	ds_write_b16 v243, v3 offset:53120
	v_fma_mixlo_f16 v3, v32, v2, 0
	ds_write_b16 v243, v3 offset:53248
	v_fma_mixlo_f16 v3, v33, v2, 0
	ds_write_b16 v243, v3 offset:53376
	v_fma_mixlo_f16 v3, v34, v2, 0
	ds_write_b16 v243, v3 offset:53504
	v_fma_mixlo_f16 v3, v35, v2, 0
	ds_write_b16 v243, v3 offset:53632
	v_fma_mixlo_f16 v3, v36, v2, 0
	ds_write_b16 v243, v3 offset:53760
	v_fma_mixlo_f16 v3, v37, v2, 0
	ds_write_b16 v243, v3 offset:53888
	v_fma_mixlo_f16 v3, v38, v2, 0
	ds_write_b16 v243, v3 offset:54016
	v_fma_mixlo_f16 v3, v39, v2, 0
	ds_write_b16 v243, v3 offset:54144
	v_fma_mixlo_f16 v3, v40, v2, 0
	ds_write_b16 v243, v3 offset:54272
	v_fma_mixlo_f16 v3, v41, v2, 0
	ds_write_b16 v243, v3 offset:54400
	v_fma_mixlo_f16 v3, v42, v2, 0
	ds_write_b16 v243, v3 offset:54528
	v_fma_mixlo_f16 v3, v43, v2, 0
	ds_write_b16 v243, v3 offset:54656
	v_fma_mixlo_f16 v3, v44, v2, 0
	ds_write_b16 v243, v3 offset:54784
	v_fma_mixlo_f16 v3, v45, v2, 0
	ds_write_b16 v243, v3 offset:54912
	v_fma_mixlo_f16 v3, v46, v2, 0
	v_fma_mixlo_f16 v2, v47, v2, 0
	ds_write_b16 v243, v2 offset:55168
	v_fma_mixlo_f16 v2, v16, v1, 0
	ds_write_b16 v243, v2 offset:55296
	v_fma_mixlo_f16 v2, v17, v1, 0
	ds_write_b16 v243, v2 offset:55424
	v_fma_mixlo_f16 v2, v18, v1, 0
	ds_write_b16 v243, v2 offset:55552
	v_fma_mixlo_f16 v2, v19, v1, 0
	ds_write_b16 v243, v2 offset:55680
	v_fma_mixlo_f16 v2, v20, v1, 0
	ds_write_b16 v243, v2 offset:55808
	v_fma_mixlo_f16 v2, v21, v1, 0
	ds_write_b16 v243, v2 offset:55936
	v_fma_mixlo_f16 v2, v22, v1, 0
	ds_write_b16 v243, v2 offset:56064
	v_fma_mixlo_f16 v2, v23, v1, 0
	ds_write_b16 v243, v2 offset:56192
	v_fma_mixlo_f16 v2, v24, v1, 0
	ds_write_b16 v243, v2 offset:56320
	v_fma_mixlo_f16 v2, v25, v1, 0
	ds_write_b16 v243, v2 offset:56448
	v_fma_mixlo_f16 v2, v26, v1, 0
	ds_write_b16 v243, v2 offset:56576
	v_fma_mixlo_f16 v2, v27, v1, 0
	ds_write_b16 v243, v2 offset:56704
	v_fma_mixlo_f16 v2, v28, v1, 0
	ds_write_b16 v243, v2 offset:56832
	v_fma_mixlo_f16 v2, v29, v1, 0
	ds_write_b16 v243, v2 offset:56960
	v_fma_mixlo_f16 v2, v30, v1, 0
	v_fma_mixlo_f16 v1, v31, v1, 0
	ds_write_b16 v243, v1 offset:57216
	v_mov_b32_e32 v1, 0x24000
	ds_write_b16 v243, v3 offset:55040
	ds_write_b16 v243, v2 offset:57088
	v_mad_i64_i32 v[2:3], s[16:17], s14, v1, v[166:167]
	v_lshl_add_u64 v[4:5], v[2:3], 0, v[142:143]
	v_lshl_add_u64 v[2:3], v[2:3], 0, v[144:145]
	global_load_dwordx4 v[112:115], v[4:5], off
	global_load_dwordx4 v[116:119], v[4:5], off offset:32
	global_load_dwordx4 v[120:123], v[2:3], off
	global_load_dwordx4 v[124:127], v[2:3], off offset:32
	v_mov_b32_e32 v2, v0
	v_mov_b32_e32 v3, v0
	v_mad_i64_i32 v[142:143], s[14:15], s14, v1, v[168:169]
	v_mov_b32_e32 v1, v0
	s_waitcnt vmcnt(5)
	v_mov_b64_e32 v[130:131], v[2:3]
	v_mov_b64_e32 v[128:129], v[0:1]
	s_and_saveexec_b64 s[14:15], s[4:5]
	s_cbranch_execz .LBB0_2054
	s_lshl_b32 s56, s29, 6
	v_lshl_add_u64 v[2:3], v[142:143], 0, s[56:57]
	global_load_dwordx4 v[128:131], v[2:3], off
